# v024 + static priority (no per-segment s_setprio flips) also in the pooling GEMM loop
# speedup vs baseline: 1.0088x; 1.0022x over previous
.LBB0_1459:
	s_ashr_i32 s23, s22, 31
	s_lshl_b64 s[16:17], s[22:23], 17
	s_add_u32 s48, s3, s16
	s_addc_u32 s49, s10, s17
	s_and_b64 s[14:15], s[14:15], exec
	v_mov_b32_e32 v2, 0
	s_cselect_b32 s16, s49, s1
	s_cselect_b32 s17, s48, s0
	s_mov_b32 s14, 0
	s_mov_b64 s[64:65], -1
	s_mov_b64 s[66:67], 0
	v_mov_b32_e32 v3, v2
	v_mov_b32_e32 v4, v2
	v_mov_b32_e32 v5, v2
	v_mov_b32_e32 v6, v2
	v_mov_b32_e32 v7, v2
	v_mov_b32_e32 v8, v2
	v_mov_b32_e32 v9, v2
	v_mov_b32_e32 v10, v2
	v_mov_b32_e32 v11, v2
	v_mov_b32_e32 v12, v2
	v_mov_b32_e32 v13, v2
	v_mov_b32_e32 v14, v2
	v_mov_b32_e32 v15, v2
	v_mov_b32_e32 v16, v2
	v_mov_b32_e32 v17, v2
	v_mov_b32_e32 v18, v2
	v_mov_b32_e32 v19, v2
	v_mov_b32_e32 v20, v2
	v_mov_b32_e32 v21, v2
	v_mov_b32_e32 v22, v2
	v_mov_b32_e32 v23, v2
	v_mov_b32_e32 v24, v2
	v_mov_b32_e32 v25, v2
	v_mov_b32_e32 v26, v2
	v_mov_b32_e32 v27, v2
	v_mov_b32_e32 v28, v2
	v_mov_b32_e32 v29, v2
	v_mov_b32_e32 v30, v2
	v_mov_b32_e32 v31, v2
	v_mov_b32_e32 v32, v2
	v_mov_b32_e32 v33, v2
	v_mov_b32_e32 v62, v2
	v_mov_b32_e32 v63, v2
	v_mov_b32_e32 v64, v2
	v_mov_b32_e32 v65, v2
	v_mov_b32_e32 v70, v2
	v_mov_b32_e32 v71, v2
	v_mov_b32_e32 v72, v2
	v_mov_b32_e32 v73, v2
	v_mov_b32_e32 v74, v2
	v_mov_b32_e32 v75, v2
	v_mov_b32_e32 v76, v2
	v_mov_b32_e32 v77, v2
	v_mov_b32_e32 v78, v2
	v_mov_b32_e32 v79, v2
	v_mov_b32_e32 v80, v2
	v_mov_b32_e32 v81, v2
	v_mov_b32_e32 v82, v2
	v_mov_b32_e32 v83, v2
	v_mov_b32_e32 v84, v2
	v_mov_b32_e32 v85, v2
	v_mov_b32_e32 v86, v2
	v_mov_b32_e32 v87, v2
	v_mov_b32_e32 v88, v2
	v_mov_b32_e32 v89, v2
	v_mov_b32_e32 v90, v2
	v_mov_b32_e32 v91, v2
	v_mov_b32_e32 v92, v2
	v_mov_b32_e32 v93, v2
	v_mov_b32_e32 v94, v2
	v_mov_b32_e32 v95, v2
	v_mov_b32_e32 v96, v2
	v_mov_b32_e32 v97, v2
	v_mov_b32_e32 v34, v2
	v_mov_b32_e32 v35, v2
	v_mov_b32_e32 v36, v2
	v_mov_b32_e32 v37, v2
	v_mov_b32_e32 v38, v2
	v_mov_b32_e32 v39, v2
	v_mov_b32_e32 v40, v2
	v_mov_b32_e32 v41, v2
	v_mov_b32_e32 v42, v2
	v_mov_b32_e32 v43, v2
	v_mov_b32_e32 v44, v2
	v_mov_b32_e32 v45, v2
	v_mov_b32_e32 v46, v2
	v_mov_b32_e32 v47, v2
	v_mov_b32_e32 v48, v2
	v_mov_b32_e32 v49, v2
	v_mov_b32_e32 v50, v2
	v_mov_b32_e32 v51, v2
	v_mov_b32_e32 v52, v2
	v_mov_b32_e32 v53, v2
	v_mov_b32_e32 v54, v2
	v_mov_b32_e32 v55, v2
	v_mov_b32_e32 v56, v2
	v_mov_b32_e32 v57, v2
	v_mov_b32_e32 v58, v2
	v_mov_b32_e32 v59, v2
	v_mov_b32_e32 v60, v2
	v_mov_b32_e32 v61, v2
	v_mov_b32_e32 v66, v2
	v_mov_b32_e32 v67, v2
	v_mov_b32_e32 v68, v2
	v_mov_b32_e32 v69, v2
	v_mov_b32_e32 v98, v2
	v_mov_b32_e32 v99, v2
	v_mov_b32_e32 v100, v2
	v_mov_b32_e32 v101, v2
	v_mov_b32_e32 v106, v2
	v_mov_b32_e32 v107, v2
	v_mov_b32_e32 v108, v2
	v_mov_b32_e32 v109, v2
	v_mov_b32_e32 v114, v2
	v_mov_b32_e32 v115, v2
	v_mov_b32_e32 v116, v2
	v_mov_b32_e32 v117, v2
	v_mov_b32_e32 v118, v2
	v_mov_b32_e32 v119, v2
	v_mov_b32_e32 v120, v2
	v_mov_b32_e32 v121, v2
	v_mov_b32_e32 v122, v2
	v_mov_b32_e32 v123, v2
	v_mov_b32_e32 v124, v2
	v_mov_b32_e32 v125, v2
	v_mov_b32_e32 v126, v2
	v_mov_b32_e32 v127, v2
	v_mov_b32_e32 v128, v2
	v_mov_b32_e32 v129, v2
	v_mov_b32_e32 v130, v2
	v_mov_b32_e32 v131, v2
	v_mov_b32_e32 v132, v2
	v_mov_b32_e32 v133, v2
	v_mov_b32_e32 v134, v2
	v_mov_b32_e32 v135, v2
	v_mov_b32_e32 v136, v2
	v_mov_b32_e32 v137, v2
.LBB0_1460:
	s_cmp_lg_u64 s[20:21], 0
	s_cbranch_scc0 .Lsp_pool1460
	s_setprio 1
.Lsp_pool1460:
	s_add_u32 s23, s50, s14
	s_addc_u32 s28, s51, 0
	s_add_u32 s15, s23, 0x100
	s_addc_u32 s29, s28, 0
	s_and_b64 s[26:27], s[66:67], exec
	s_cselect_b32 s71, s43, s29
	s_cselect_b32 s70, s42, s15
	s_add_u32 s14, s0, s14
	s_addc_u32 s15, s1, 0
	s_add_u32 s26, s14, 0x100
	s_addc_u32 s27, s15, 0
	s_add_i32 s35, 0, 0x10000
	s_and_b64 s[14:15], s[66:67], exec
	s_cselect_b32 s15, s16, s27
	s_cselect_b32 s14, s17, s26
	s_add_i32 s39, 0, 0x14000
	s_add_u32 s74, s23, 0x40080
	s_addc_u32 s75, s28, 0
	s_add_i32 s34, s35, s11
	s_add_i32 m0, s53, 0xc000
	s_add_i32 s41, s53, 0xe000
	s_add_i32 s29, s34, 0x2000
	v_add_u32_e32 v151, s35, v148
	s_add_u32 s72, s14, 0x10000
	ds_read_b128 v[102:105], v151
	ds_read_b128 v[110:113], v151 offset:1024
	ds_read_b128 v[144:147], v151 offset:2048
	ds_read_b128 v[152:155], v151 offset:3072
	v_add_u32_e32 v151, s39, v148
	s_addc_u32 s73, s15, 0
	s_add_i32 s31, s39, s11
	ds_read_b128 v[168:171], v151
	ds_read_b128 v[172:175], v151 offset:1024
	ds_read_b128 v[176:179], v151 offset:2048
	ds_read_b128 v[180:183], v151 offset:3072
	s_add_i32 s30, s31, 0x2000
	s_add_i32 s28, 0, 0x18000
	s_add_i32 s27, 0, 0x1c000
	s_add_u32 s68, s70, 0x40000
	s_addc_u32 s69, s71, 0
	s_add_i32 s26, s28, s11
	s_add_i32 s23, s26, 0x2000
	s_add_u32 s66, s14, 0x10080
	s_addc_u32 s67, s15, 0
	s_add_i32 s39, s27, s11
	s_add_i32 s35, s39, 0x2000
	v_lshl_add_u64 v[156:157], s[74:75], 0, v[142:143]
	ds_read_b128 v[184:187], v150
	ds_read_b128 v[188:191], v150 offset:1024
	ds_read_b128 v[192:195], v150 offset:2048
	ds_read_b128 v[196:199], v150 offset:3072
	ds_read_b128 v[200:203], v150 offset:4096
	ds_read_b128 v[204:207], v150 offset:5120
	ds_read_b128 v[216:219], v150 offset:6144
	ds_read_b128 v[220:223], v150 offset:7168
	global_load_lds_dwordx4 v[156:157], off
	v_lshl_add_u64 v[156:157], s[74:75], 0, v[140:141]
	s_mov_b32 m0, s41
	s_nop 0
	global_load_lds_dwordx4 v[156:157], off
	s_waitcnt vmcnt(8)
	s_waitcnt lgkmcnt(0)
	s_barrier
	s_waitcnt lgkmcnt(0)
	v_mfma_f32_16x16x32_bf16 v[134:137], v[102:105], v[184:187], v[134:137]
	v_mfma_f32_16x16x32_bf16 v[134:137], v[110:113], v[188:191], v[134:137]
	v_mfma_f32_16x16x32_bf16 v[130:133], v[144:147], v[184:187], v[130:133]
	v_mfma_f32_16x16x32_bf16 v[130:133], v[152:155], v[188:191], v[130:133]
	v_mfma_f32_16x16x32_bf16 v[126:129], v[102:105], v[192:195], v[126:129]
	v_mfma_f32_16x16x32_bf16 v[126:129], v[110:113], v[196:199], v[126:129]
	v_mfma_f32_16x16x32_bf16 v[122:125], v[144:147], v[192:195], v[122:125]
	v_mfma_f32_16x16x32_bf16 v[122:125], v[152:155], v[196:199], v[122:125]
	v_mfma_f32_16x16x32_bf16 v[118:121], v[102:105], v[200:203], v[118:121]
	v_mfma_f32_16x16x32_bf16 v[118:121], v[110:113], v[204:207], v[118:121]
	v_mfma_f32_16x16x32_bf16 v[114:117], v[144:147], v[200:203], v[114:117]
	v_mfma_f32_16x16x32_bf16 v[114:117], v[152:155], v[204:207], v[114:117]
	v_mfma_f32_16x16x32_bf16 v[106:109], v[102:105], v[216:219], v[106:109]
	v_mfma_f32_16x16x32_bf16 v[106:109], v[110:113], v[220:223], v[106:109]
	v_mfma_f32_16x16x32_bf16 v[98:101], v[144:147], v[216:219], v[98:101]
	v_mfma_f32_16x16x32_bf16 v[98:101], v[152:155], v[220:223], v[98:101]
	v_mfma_f32_16x16x32_bf16 v[66:69], v[168:171], v[184:187], v[66:69]
	v_mfma_f32_16x16x32_bf16 v[66:69], v[172:175], v[188:191], v[66:69]
	v_mfma_f32_16x16x32_bf16 v[58:61], v[176:179], v[184:187], v[58:61]
	v_mfma_f32_16x16x32_bf16 v[58:61], v[180:183], v[188:191], v[58:61]
	v_mfma_f32_16x16x32_bf16 v[54:57], v[168:171], v[192:195], v[54:57]
	v_mfma_f32_16x16x32_bf16 v[54:57], v[172:175], v[196:199], v[54:57]
	v_mfma_f32_16x16x32_bf16 v[50:53], v[176:179], v[192:195], v[50:53]
	v_mfma_f32_16x16x32_bf16 v[50:53], v[180:183], v[196:199], v[50:53]
	v_mfma_f32_16x16x32_bf16 v[46:49], v[168:171], v[200:203], v[46:49]
	v_mfma_f32_16x16x32_bf16 v[46:49], v[172:175], v[204:207], v[46:49]
	v_mfma_f32_16x16x32_bf16 v[42:45], v[176:179], v[200:203], v[42:45]
	v_mfma_f32_16x16x32_bf16 v[42:45], v[180:183], v[204:207], v[42:45]
	v_mfma_f32_16x16x32_bf16 v[38:41], v[168:171], v[216:219], v[38:41]
	v_mfma_f32_16x16x32_bf16 v[38:41], v[172:175], v[220:223], v[38:41]
	v_mfma_f32_16x16x32_bf16 v[34:37], v[176:179], v[216:219], v[34:37]
	v_mfma_f32_16x16x32_bf16 v[34:37], v[180:183], v[220:223], v[34:37]
	s_barrier
	s_mov_b32 m0, s34
	v_lshl_add_u64 v[156:157], s[14:15], 0, v[158:159]
	ds_read_b128 v[184:187], v150 offset:16384
	ds_read_b128 v[188:191], v150 offset:17408
	ds_read_b128 v[192:195], v150 offset:18432
	ds_read_b128 v[196:199], v150 offset:19456
	ds_read_b128 v[200:203], v150 offset:20480
	ds_read_b128 v[204:207], v150 offset:21504
	ds_read_b128 v[216:219], v150 offset:22528
	ds_read_b128 v[220:223], v150 offset:23552
	global_load_lds_dwordx4 v[156:157], off
	v_lshl_add_u64 v[224:225], s[14:15], 0, v[138:139]
	s_mov_b32 m0, s29
	v_lshl_add_u64 v[226:227], s[72:73], 0, v[158:159]
	global_load_lds_dwordx4 v[224:225], off
	s_mov_b32 m0, s31
	v_lshl_add_u64 v[228:229], s[70:71], 0, v[140:141]
	global_load_lds_dwordx4 v[226:227], off
	v_lshl_add_u64 v[226:227], s[72:73], 0, v[138:139]
	s_mov_b32 m0, s30
	s_nop 0
	global_load_lds_dwordx4 v[226:227], off
	v_lshl_add_u64 v[226:227], s[70:71], 0, v[142:143]
	s_mov_b32 m0, s53
	s_nop 0
	global_load_lds_dwordx4 v[226:227], off
	s_mov_b32 m0, s58
	s_nop 0
	global_load_lds_dwordx4 v[228:229], off
	s_waitcnt vmcnt(8)
	s_waitcnt lgkmcnt(0)
	s_barrier
	s_waitcnt lgkmcnt(0)
	v_mfma_f32_16x16x32_bf16 v[94:97], v[102:105], v[184:187], v[94:97]
	v_mfma_f32_16x16x32_bf16 v[94:97], v[110:113], v[188:191], v[94:97]
	v_mfma_f32_16x16x32_bf16 v[90:93], v[144:147], v[184:187], v[90:93]
	v_mfma_f32_16x16x32_bf16 v[90:93], v[152:155], v[188:191], v[90:93]
	v_mfma_f32_16x16x32_bf16 v[86:89], v[102:105], v[192:195], v[86:89]
	v_mfma_f32_16x16x32_bf16 v[86:89], v[110:113], v[196:199], v[86:89]
	v_mfma_f32_16x16x32_bf16 v[82:85], v[144:147], v[192:195], v[82:85]
	v_mfma_f32_16x16x32_bf16 v[82:85], v[152:155], v[196:199], v[82:85]
	v_mfma_f32_16x16x32_bf16 v[78:81], v[102:105], v[200:203], v[78:81]
	v_mfma_f32_16x16x32_bf16 v[78:81], v[110:113], v[204:207], v[78:81]
	v_mfma_f32_16x16x32_bf16 v[74:77], v[144:147], v[200:203], v[74:77]
	v_mfma_f32_16x16x32_bf16 v[74:77], v[152:155], v[204:207], v[74:77]
	v_mfma_f32_16x16x32_bf16 v[70:73], v[102:105], v[216:219], v[70:73]
	v_mfma_f32_16x16x32_bf16 v[70:73], v[110:113], v[220:223], v[70:73]
	v_mfma_f32_16x16x32_bf16 v[62:65], v[144:147], v[216:219], v[62:65]
	v_mfma_f32_16x16x32_bf16 v[62:65], v[152:155], v[220:223], v[62:65]
	v_mfma_f32_16x16x32_bf16 v[30:33], v[168:171], v[184:187], v[30:33]
	v_mfma_f32_16x16x32_bf16 v[30:33], v[172:175], v[188:191], v[30:33]
	v_mfma_f32_16x16x32_bf16 v[26:29], v[176:179], v[184:187], v[26:29]
	v_mfma_f32_16x16x32_bf16 v[26:29], v[180:183], v[188:191], v[26:29]
	v_mfma_f32_16x16x32_bf16 v[22:25], v[168:171], v[192:195], v[22:25]
	v_mfma_f32_16x16x32_bf16 v[22:25], v[172:175], v[196:199], v[22:25]
	v_mfma_f32_16x16x32_bf16 v[18:21], v[176:179], v[192:195], v[18:21]
	v_mfma_f32_16x16x32_bf16 v[18:21], v[180:183], v[196:199], v[18:21]
	v_mfma_f32_16x16x32_bf16 v[14:17], v[168:171], v[200:203], v[14:17]
	v_mfma_f32_16x16x32_bf16 v[14:17], v[172:175], v[204:207], v[14:17]
	v_mfma_f32_16x16x32_bf16 v[10:13], v[176:179], v[200:203], v[10:13]
	v_mfma_f32_16x16x32_bf16 v[10:13], v[180:183], v[204:207], v[10:13]
	v_mfma_f32_16x16x32_bf16 v[6:9], v[168:171], v[216:219], v[6:9]
	v_mfma_f32_16x16x32_bf16 v[6:9], v[172:175], v[220:223], v[6:9]
	v_mfma_f32_16x16x32_bf16 v[2:5], v[176:179], v[216:219], v[2:5]
	v_mfma_f32_16x16x32_bf16 v[2:5], v[180:183], v[220:223], v[2:5]
	s_barrier
	v_add_u32_e32 v151, s28, v148
	ds_read_b128 v[102:105], v151
	ds_read_b128 v[110:113], v151 offset:1024
	ds_read_b128 v[144:147], v151 offset:2048
	ds_read_b128 v[152:155], v151 offset:3072
	v_add_u32_e32 v151, s27, v148
	ds_read_b128 v[168:171], v151
	ds_read_b128 v[172:175], v151 offset:1024
	ds_read_b128 v[176:179], v151 offset:2048
	ds_read_b128 v[180:183], v151 offset:3072
	s_mov_b32 m0, s59
	v_lshl_add_u64 v[230:231], s[68:69], 0, v[142:143]
	ds_read_b128 v[184:187], v150 offset:32768
	ds_read_b128 v[188:191], v150 offset:33792
	ds_read_b128 v[192:195], v150 offset:34816
	ds_read_b128 v[196:199], v150 offset:35840
	ds_read_b128 v[200:203], v150 offset:36864
	ds_read_b128 v[204:207], v150 offset:37888
	ds_read_b128 v[216:219], v150 offset:38912
	ds_read_b128 v[220:223], v150 offset:39936
	global_load_lds_dwordx4 v[230:231], off
	v_lshl_add_u64 v[230:231], s[68:69], 0, v[140:141]
	s_mov_b32 m0, s92
	s_nop 0
	global_load_lds_dwordx4 v[230:231], off
	s_waitcnt vmcnt(8)
	s_waitcnt lgkmcnt(0)
	s_barrier
	s_waitcnt lgkmcnt(0)
	v_mfma_f32_16x16x32_bf16 v[134:137], v[102:105], v[184:187], v[134:137]
	v_mfma_f32_16x16x32_bf16 v[134:137], v[110:113], v[188:191], v[134:137]
	v_mfma_f32_16x16x32_bf16 v[130:133], v[144:147], v[184:187], v[130:133]
	v_mfma_f32_16x16x32_bf16 v[130:133], v[152:155], v[188:191], v[130:133]
	v_mfma_f32_16x16x32_bf16 v[126:129], v[102:105], v[192:195], v[126:129]
	v_mfma_f32_16x16x32_bf16 v[126:129], v[110:113], v[196:199], v[126:129]
	v_mfma_f32_16x16x32_bf16 v[122:125], v[144:147], v[192:195], v[122:125]
	v_mfma_f32_16x16x32_bf16 v[122:125], v[152:155], v[196:199], v[122:125]
	v_mfma_f32_16x16x32_bf16 v[118:121], v[102:105], v[200:203], v[118:121]
	v_mfma_f32_16x16x32_bf16 v[118:121], v[110:113], v[204:207], v[118:121]
	v_mfma_f32_16x16x32_bf16 v[114:117], v[144:147], v[200:203], v[114:117]
	v_mfma_f32_16x16x32_bf16 v[114:117], v[152:155], v[204:207], v[114:117]
	v_mfma_f32_16x16x32_bf16 v[106:109], v[102:105], v[216:219], v[106:109]
	v_mfma_f32_16x16x32_bf16 v[106:109], v[110:113], v[220:223], v[106:109]
	v_mfma_f32_16x16x32_bf16 v[98:101], v[144:147], v[216:219], v[98:101]
	v_mfma_f32_16x16x32_bf16 v[98:101], v[152:155], v[220:223], v[98:101]
	v_mfma_f32_16x16x32_bf16 v[66:69], v[168:171], v[184:187], v[66:69]
	v_mfma_f32_16x16x32_bf16 v[66:69], v[172:175], v[188:191], v[66:69]
	v_mfma_f32_16x16x32_bf16 v[58:61], v[176:179], v[184:187], v[58:61]
	v_mfma_f32_16x16x32_bf16 v[58:61], v[180:183], v[188:191], v[58:61]
	v_mfma_f32_16x16x32_bf16 v[54:57], v[168:171], v[192:195], v[54:57]
	v_mfma_f32_16x16x32_bf16 v[54:57], v[172:175], v[196:199], v[54:57]
	v_mfma_f32_16x16x32_bf16 v[50:53], v[176:179], v[192:195], v[50:53]
	v_mfma_f32_16x16x32_bf16 v[50:53], v[180:183], v[196:199], v[50:53]
	v_mfma_f32_16x16x32_bf16 v[46:49], v[168:171], v[200:203], v[46:49]
	v_mfma_f32_16x16x32_bf16 v[46:49], v[172:175], v[204:207], v[46:49]
	v_mfma_f32_16x16x32_bf16 v[42:45], v[176:179], v[200:203], v[42:45]
	v_mfma_f32_16x16x32_bf16 v[42:45], v[180:183], v[204:207], v[42:45]
	v_mfma_f32_16x16x32_bf16 v[38:41], v[168:171], v[216:219], v[38:41]
	v_mfma_f32_16x16x32_bf16 v[38:41], v[172:175], v[220:223], v[38:41]
	v_mfma_f32_16x16x32_bf16 v[34:37], v[176:179], v[216:219], v[34:37]
	v_mfma_f32_16x16x32_bf16 v[34:37], v[180:183], v[220:223], v[34:37]
	s_barrier
	s_mov_b32 m0, s26
	v_lshl_add_u64 v[156:157], v[156:157], 0, s[56:57]
	ds_read_b128 v[184:187], v150 offset:49152
	ds_read_b128 v[188:191], v150 offset:50176
	ds_read_b128 v[192:195], v150 offset:51200
	ds_read_b128 v[196:199], v150 offset:52224
	ds_read_b128 v[200:203], v150 offset:53248
	ds_read_b128 v[204:207], v150 offset:54272
	ds_read_b128 v[216:219], v150 offset:55296
	ds_read_b128 v[220:223], v150 offset:56320
	global_load_lds_dwordx4 v[156:157], off
	v_lshl_add_u64 v[156:157], v[224:225], 0, s[56:57]
	s_mov_b32 m0, s23
	s_nop 0
	global_load_lds_dwordx4 v[156:157], off
	v_lshl_add_u64 v[156:157], s[66:67], 0, v[158:159]
	s_mov_b32 m0, s39
	s_nop 0
	global_load_lds_dwordx4 v[156:157], off
	v_lshl_add_u64 v[156:157], s[66:67], 0, v[138:139]
	s_mov_b32 m0, s35
	s_nop 0
	global_load_lds_dwordx4 v[156:157], off
	v_lshl_add_u64 v[156:157], v[226:227], 0, s[56:57]
	s_mov_b32 m0, s54
	s_nop 0
	global_load_lds_dwordx4 v[156:157], off
	v_lshl_add_u64 v[156:157], v[228:229], 0, s[56:57]
	s_mov_b32 m0, s60
	s_nop 0
	global_load_lds_dwordx4 v[156:157], off
	s_waitcnt vmcnt(8)
	s_waitcnt lgkmcnt(0)
	s_barrier
	s_waitcnt lgkmcnt(0)
	v_mfma_f32_16x16x32_bf16 v[94:97], v[102:105], v[184:187], v[94:97]
	v_mfma_f32_16x16x32_bf16 v[94:97], v[110:113], v[188:191], v[94:97]
	v_mfma_f32_16x16x32_bf16 v[90:93], v[144:147], v[184:187], v[90:93]
	v_mfma_f32_16x16x32_bf16 v[90:93], v[152:155], v[188:191], v[90:93]
	v_mfma_f32_16x16x32_bf16 v[86:89], v[102:105], v[192:195], v[86:89]
	v_mfma_f32_16x16x32_bf16 v[86:89], v[110:113], v[196:199], v[86:89]
	v_mfma_f32_16x16x32_bf16 v[82:85], v[144:147], v[192:195], v[82:85]
	v_mfma_f32_16x16x32_bf16 v[82:85], v[152:155], v[196:199], v[82:85]
	v_mfma_f32_16x16x32_bf16 v[78:81], v[102:105], v[200:203], v[78:81]
	v_mfma_f32_16x16x32_bf16 v[78:81], v[110:113], v[204:207], v[78:81]
	v_mfma_f32_16x16x32_bf16 v[74:77], v[144:147], v[200:203], v[74:77]
	v_mfma_f32_16x16x32_bf16 v[74:77], v[152:155], v[204:207], v[74:77]
	v_mfma_f32_16x16x32_bf16 v[70:73], v[102:105], v[216:219], v[70:73]
	v_mfma_f32_16x16x32_bf16 v[70:73], v[110:113], v[220:223], v[70:73]
	v_mfma_f32_16x16x32_bf16 v[62:65], v[144:147], v[216:219], v[62:65]
	v_mfma_f32_16x16x32_bf16 v[62:65], v[152:155], v[220:223], v[62:65]
	v_mfma_f32_16x16x32_bf16 v[30:33], v[168:171], v[184:187], v[30:33]
	v_mfma_f32_16x16x32_bf16 v[30:33], v[172:175], v[188:191], v[30:33]
	v_mfma_f32_16x16x32_bf16 v[26:29], v[176:179], v[184:187], v[26:29]
	v_mfma_f32_16x16x32_bf16 v[26:29], v[180:183], v[188:191], v[26:29]
	v_mfma_f32_16x16x32_bf16 v[22:25], v[168:171], v[192:195], v[22:25]
	v_mfma_f32_16x16x32_bf16 v[22:25], v[172:175], v[196:199], v[22:25]
	v_mfma_f32_16x16x32_bf16 v[18:21], v[176:179], v[192:195], v[18:21]
	v_mfma_f32_16x16x32_bf16 v[18:21], v[180:183], v[196:199], v[18:21]
	v_mfma_f32_16x16x32_bf16 v[14:17], v[168:171], v[200:203], v[14:17]
	v_mfma_f32_16x16x32_bf16 v[14:17], v[172:175], v[204:207], v[14:17]
	v_mfma_f32_16x16x32_bf16 v[10:13], v[176:179], v[200:203], v[10:13]
	v_mfma_f32_16x16x32_bf16 v[10:13], v[180:183], v[204:207], v[10:13]
	v_mfma_f32_16x16x32_bf16 v[6:9], v[168:171], v[216:219], v[6:9]
	v_mfma_f32_16x16x32_bf16 v[6:9], v[172:175], v[220:223], v[6:9]
	v_mfma_f32_16x16x32_bf16 v[2:5], v[176:179], v[216:219], v[2:5]
	v_mfma_f32_16x16x32_bf16 v[2:5], v[180:183], v[220:223], v[2:5]
	s_barrier
	s_movk_i32 s14, 0x100
	s_andn2_b64 vcc, exec, s[64:65]
	s_mov_b64 s[66:67], -1
	s_mov_b64 s[64:65], 0
	s_cbranch_vccz .LBB0_1460
	s_and_b64 vcc, exec, s[20:21]
	s_cbranch_vccz .LBB0_1463
	s_barrier
